# cmp1 GEMM: 4-stage register ring for global loads with static offsets, 5 A-fragment buffers
# baseline (speedup 1.0000x reference)
; template <int MI, int NJ> ...
;     ...
;   if (!pre) G8LOADP(Ag, Bg);
;   G8STORE(0);
;   {
;     const u16* ga_ = (1 < nk) ? Ag + 64 : Ag + nAoff;
;     const u16* gb_ = (1 < nk) ? Bg + 64 : Bg + nBoff;
;     G8LOADP(ga_, gb_);
;   }
;   __syncthreads();
; __device__ __forceinline__ void phase_cmp1(const Params& p, u16* smem, volatile LAS unsigned* vb_) {
;     ...
;   for (int it = vb; it < 64; it += gridDim.x) {
;     const int m = it >> 5, mt = (it >> 1) & 15, nt = it & 1;
;     const u16* A = (const u16*)(p.ws + OFF_CMPA) + (size_t)m * 2048 * 2048;
;     const u16* Bt = (const u16*)(p.ws + W_C1) + (size_t)m * 256 * 2048;
;     u16* Hc = (u16*)(p.ws + OFF_HC) + (size_t)m * 2048 * 256;
;     f32x4 acc[4][2];
; #pragma unroll
;     for (int i = 0; i < 4; ++i)
; #pragma unroll
;       for (int j = 0; j < 2; ++j) acc[i][j] = (f32x4){0.f, 0.f, 0.f, 0.f};
;     {
;       G8REGS_DECL;
;       R_a2 = R_a3 = R_b2 = R_b3 = make_uint4(0u, 0u, 0u, 0u);
;       gemm8<4, 2>(acc, G8REGS_ARGS, false, A, 2048, Bt, 2048, 0, 2048, mt * 128, nt * 128, mt * 128, nt * 128, 0, smem, tid);
.LBB0_435:
	s_ashr_i32 s0, s10, 5
	s_ashr_i32 s1, s0, 31
	s_lshl_b64 s[12:13], s[0:1], 23
	s_add_u32 s12, s34, s12
	s_addc_u32 s13, s35, s13
	s_lshl_b64 s[0:1], s[0:1], 20
	v_readlane_b32 s11, v253, 5
	s_add_u32 s22, s11, s0
	v_readlane_b32 s11, v253, 6
	s_addc_u32 s23, s11, s1
	s_lshl_b32 s11, s10, 6
	s_and_b32 s11, s11, 0x780
	v_add_u32_e32 v2, s11, v54
	v_ashrrev_i32_e32 v3, 31, v2
	s_lshl_b32 s20, s10, 7
	v_lshlrev_b64 v[2:3], 12, v[2:3]
	s_and_b32 s20, s20, 0x80
	v_lshl_add_u64 v[2:3], s[12:13], 0, v[2:3]
	v_lshl_add_u64 v[50:51], v[2:3], 0, v[0:1]
	v_add_u32_e32 v2, s20, v54
	v_ashrrev_i32_e32 v3, 31, v2
	v_lshlrev_b64 v[2:3], 12, v[2:3]
	v_add_co_u32_e32 v18, vcc, s14, v50
	v_lshl_add_u64 v[2:3], s[22:23], 0, v[2:3]
	s_nop 0
	v_addc_co_u32_e32 v19, vcc, 0, v51, vcc
	v_lshl_add_u64 v[52:53], v[2:3], 0, v[0:1]
	s_mov_b64 s[12:13], 0x40000
	v_lshl_add_u64 v[148:149], v[50:51], 0, s[12:13]
	v_lshl_add_u64 v[150:151], v[52:53], 0, s[12:13]
	global_load_dwordx4 v[34:37], v[50:51], off
	global_load_dwordx4 v[38:41], v[148:149], off
	global_load_dwordx4 v[42:45], v[52:53], off
	global_load_dwordx4 v[46:49], v[150:151], off
	global_load_dwordx4 v[76:79], v[50:51], off offset:128
	global_load_dwordx4 v[80:83], v[148:149], off offset:128
	global_load_dwordx4 v[84:87], v[52:53], off offset:128
	global_load_dwordx4 v[88:91], v[150:151], off offset:128
	global_load_dwordx4 v[92:95], v[50:51], off offset:256
	global_load_dwordx4 v[96:99], v[148:149], off offset:256
	global_load_dwordx4 v[100:103], v[52:53], off offset:256
	global_load_dwordx4 v[104:107], v[150:151], off offset:256
	global_load_dwordx4 v[108:111], v[50:51], off offset:384
	global_load_dwordx4 v[112:115], v[148:149], off offset:384
	global_load_dwordx4 v[116:119], v[52:53], off offset:384
	global_load_dwordx4 v[120:123], v[150:151], off offset:384
	s_mov_b32 s21, 0
	s_waitcnt vmcnt(12)
	ds_write_b128 v55, v[34:37]
	ds_write_b128 v55, v[38:41] offset:8192
	ds_write_b128 v55, v[42:45] offset:32768
	ds_write_b128 v55, v[46:49] offset:40960
	global_load_dwordx4 v[34:37], v[50:51], off offset:512
	global_load_dwordx4 v[38:41], v[148:149], off offset:512
	global_load_dwordx4 v[42:45], v[52:53], off offset:512
	global_load_dwordx4 v[46:49], v[150:151], off offset:512
	v_mov_b32_e32 v2, 0
	v_mov_b32_e32 v3, v2
	v_mov_b32_e32 v4, v2
	v_mov_b32_e32 v5, v2
	v_mov_b32_e32 v6, v2
	v_mov_b32_e32 v7, v2
	v_mov_b32_e32 v8, v2
	v_mov_b32_e32 v9, v2
	v_mov_b32_e32 v10, v2
	v_mov_b32_e32 v11, v2
	v_mov_b32_e32 v12, v2
	v_mov_b32_e32 v13, v2
	v_mov_b32_e32 v14, v2
	v_mov_b32_e32 v15, v2
	v_mov_b32_e32 v16, v2
	v_mov_b32_e32 v17, v2
	v_mov_b32_e32 v18, v2
	v_mov_b32_e32 v19, v2
	v_mov_b32_e32 v20, v2
	v_mov_b32_e32 v21, v2
	v_mov_b32_e32 v22, v2
	v_mov_b32_e32 v23, v2
	v_mov_b32_e32 v24, v2
	v_mov_b32_e32 v25, v2
	v_mov_b32_e32 v26, v2
	v_mov_b32_e32 v27, v2
	v_mov_b32_e32 v28, v2
	v_mov_b32_e32 v29, v2
	v_mov_b32_e32 v30, v2
	v_mov_b32_e32 v31, v2
	v_mov_b32_e32 v32, v2
	v_mov_b32_e32 v33, v2
	s_waitcnt lgkmcnt(0)
	s_barrier
.LBB0_436:
	s_waitcnt vmcnt(12)
	ds_write_b128 v55, v[76:79] offset:16384
	ds_write_b128 v55, v[80:83] offset:24576
	ds_write_b128 v55, v[84:87] offset:49152
	ds_write_b128 v55, v[88:91] offset:57344
	global_load_dwordx4 v[76:79], v[50:51], off offset:640
	global_load_dwordx4 v[80:83], v[148:149], off offset:640
	global_load_dwordx4 v[84:87], v[52:53], off offset:640
	global_load_dwordx4 v[88:91], v[150:151], off offset:640
	s_setprio 1
	ds_read_b128 v[68:71], v58 offset:32768
	ds_read_b128 v[64:67], v56
	ds_read_b128 v[72:75], v58 offset:34816
	ds_read_b128 v[124:127], v56 offset:2048
	ds_read_b128 v[128:131], v56 offset:4096
	ds_read_b128 v[132:135], v56 offset:6144
	ds_read_b128 v[136:139], v61
	s_waitcnt lgkmcnt(5)
	v_mfma_f32_16x16x32_bf16 v[30:33], v[64:67], v[68:71], v[30:33]
	s_waitcnt lgkmcnt(4)
	v_mfma_f32_16x16x32_bf16 v[26:29], v[64:67], v[72:75], v[26:29]
	ds_read_b128 v[64:67], v61 offset:2048
	s_waitcnt lgkmcnt(4)
	v_mfma_f32_16x16x32_bf16 v[22:25], v[124:127], v[68:71], v[22:25]
	v_mfma_f32_16x16x32_bf16 v[18:21], v[124:127], v[72:75], v[18:21]
	ds_read_b128 v[124:127], v61 offset:4096
	ds_read_b128 v[140:143], v60 offset:32768
	ds_read_b128 v[144:147], v60 offset:34816
	s_waitcnt lgkmcnt(6)
	v_mfma_f32_16x16x32_bf16 v[14:17], v[128:131], v[68:71], v[14:17]
	v_mfma_f32_16x16x32_bf16 v[10:13], v[128:131], v[72:75], v[10:13]
	ds_read_b128 v[128:131], v61 offset:6144
	s_waitcnt lgkmcnt(6)
	v_mfma_f32_16x16x32_bf16 v[6:9], v[132:135], v[68:71], v[6:9]
	v_mfma_f32_16x16x32_bf16 v[2:5], v[132:135], v[72:75], v[2:5]
	s_waitcnt lgkmcnt(1)
	v_mfma_f32_16x16x32_bf16 v[30:33], v[136:139], v[140:143], v[30:33]
	v_mfma_f32_16x16x32_bf16 v[26:29], v[136:139], v[144:147], v[26:29]
	s_waitcnt lgkmcnt(4)
	v_mfma_f32_16x16x32_bf16 v[22:25], v[64:67], v[140:143], v[22:25]
	v_mfma_f32_16x16x32_bf16 v[18:21], v[64:67], v[144:147], v[18:21]
	s_waitcnt lgkmcnt(3)
	v_mfma_f32_16x16x32_bf16 v[14:17], v[124:127], v[140:143], v[14:17]
	v_mfma_f32_16x16x32_bf16 v[10:13], v[124:127], v[144:147], v[10:13]
	s_waitcnt lgkmcnt(0)
	v_mfma_f32_16x16x32_bf16 v[6:9], v[128:131], v[140:143], v[6:9]
	v_mfma_f32_16x16x32_bf16 v[2:5], v[128:131], v[144:147], v[2:5]
	s_setprio 0
	s_barrier
; template <int MI, int NJ> ...
;     ...
;   for (int kt = 0; kt < nk; ++kt) {
;     const int buf = kt & 1;
;     {
;       G8STORE(buf ^ 1);
;       const u16* ga_ = (kt + 2 < nk) ? Ag + (kt + 2) * 64 : Ag + nAoff;
;       const u16* gb_ = (kt + 2 < nk) ? Bg + (kt + 2) * 64 : Bg + nBoff;
;       G8LOADP(ga_, gb_);
;     }
;     __builtin_amdgcn_sched_barrier(0);
;     __builtin_amdgcn_s_setprio(1);
;     const u16* a = ra_ + buf * AROWS * 64;
;     const u16* b = rb_ + buf * BROWS * 64;
; #pragma unroll
;     for (int ks = 0; ks < 2; ++ks) {
;       const u16* a_ = ks ? a + dsw : a;
;       const u16* b_ = ks ? b + dsw : b;
;       bf16x8 bfr[NJ];
; #pragma unroll
;       for (int j = 0; j < NJ; ++j) bfr[j] = *(const bf16x8*)(b_ + j * 16 * 64);
; #pragma unroll
;       for (int ih = 0; ih < MI / 4; ++ih) {
;         bf16x8 af[4];
; #pragma unroll
;         for (int i = 0; i < 4; ++i) af[i] = *(const bf16x8*)(a_ + (ih * 4 + i) * 16 * 64);
; #pragma unroll
;         for (int i = 0; i < 4; ++i)
; #pragma unroll
;           for (int j = 0; j < NJ; ++j) acc[ih * 4 + i][j] = mfma16(af[i], bfr[j], acc[ih * 4 + i][j]);
;       }
;     }
;     __builtin_amdgcn_s_setprio(0);
;     __builtin_amdgcn_sched_barrier(0);
;     __syncthreads();
	s_waitcnt vmcnt(12)
	ds_write_b128 v55, v[92:95]
	ds_write_b128 v55, v[96:99] offset:8192
	ds_write_b128 v55, v[100:103] offset:32768
	ds_write_b128 v55, v[104:107] offset:40960
	global_load_dwordx4 v[92:95], v[50:51], off offset:768
	global_load_dwordx4 v[96:99], v[148:149], off offset:768
	global_load_dwordx4 v[100:103], v[52:53], off offset:768
	global_load_dwordx4 v[104:107], v[150:151], off offset:768
	s_setprio 1
	ds_read_b128 v[68:71], v58 offset:49152
	ds_read_b128 v[64:67], v56 offset:16384
	ds_read_b128 v[72:75], v58 offset:51200
	ds_read_b128 v[124:127], v56 offset:18432
	ds_read_b128 v[128:131], v56 offset:20480
	ds_read_b128 v[132:135], v56 offset:22528
	ds_read_b128 v[136:139], v61 offset:16384
	s_waitcnt lgkmcnt(5)
	v_mfma_f32_16x16x32_bf16 v[30:33], v[64:67], v[68:71], v[30:33]
	s_waitcnt lgkmcnt(4)
	v_mfma_f32_16x16x32_bf16 v[26:29], v[64:67], v[72:75], v[26:29]
	ds_read_b128 v[64:67], v61 offset:18432
	s_waitcnt lgkmcnt(4)
	v_mfma_f32_16x16x32_bf16 v[22:25], v[124:127], v[68:71], v[22:25]
	v_mfma_f32_16x16x32_bf16 v[18:21], v[124:127], v[72:75], v[18:21]
	ds_read_b128 v[124:127], v61 offset:20480
	ds_read_b128 v[140:143], v60 offset:49152
	ds_read_b128 v[144:147], v60 offset:51200
	s_waitcnt lgkmcnt(6)
	v_mfma_f32_16x16x32_bf16 v[14:17], v[128:131], v[68:71], v[14:17]
	v_mfma_f32_16x16x32_bf16 v[10:13], v[128:131], v[72:75], v[10:13]
	ds_read_b128 v[128:131], v61 offset:22528
	s_waitcnt lgkmcnt(6)
	v_mfma_f32_16x16x32_bf16 v[6:9], v[132:135], v[68:71], v[6:9]
	v_mfma_f32_16x16x32_bf16 v[2:5], v[132:135], v[72:75], v[2:5]
	s_waitcnt lgkmcnt(1)
	v_mfma_f32_16x16x32_bf16 v[30:33], v[136:139], v[140:143], v[30:33]
	v_mfma_f32_16x16x32_bf16 v[26:29], v[136:139], v[144:147], v[26:29]
	s_waitcnt lgkmcnt(4)
	v_mfma_f32_16x16x32_bf16 v[22:25], v[64:67], v[140:143], v[22:25]
	v_mfma_f32_16x16x32_bf16 v[18:21], v[64:67], v[144:147], v[18:21]
	s_waitcnt lgkmcnt(3)
	v_mfma_f32_16x16x32_bf16 v[14:17], v[124:127], v[140:143], v[14:17]
	v_mfma_f32_16x16x32_bf16 v[10:13], v[124:127], v[144:147], v[10:13]
	s_waitcnt lgkmcnt(0)
	v_mfma_f32_16x16x32_bf16 v[6:9], v[128:131], v[140:143], v[6:9]
	v_mfma_f32_16x16x32_bf16 v[2:5], v[128:131], v[144:147], v[2:5]
	s_setprio 0
	s_barrier
	s_waitcnt vmcnt(12)
	ds_write_b128 v55, v[108:111] offset:16384
	ds_write_b128 v55, v[112:115] offset:24576
	ds_write_b128 v55, v[116:119] offset:49152
	ds_write_b128 v55, v[120:123] offset:57344
	global_load_dwordx4 v[108:111], v[50:51], off offset:896
	global_load_dwordx4 v[112:115], v[148:149], off offset:896
	global_load_dwordx4 v[116:119], v[52:53], off offset:896
	global_load_dwordx4 v[120:123], v[150:151], off offset:896
	s_setprio 1
	ds_read_b128 v[68:71], v58 offset:32768
	ds_read_b128 v[64:67], v56
	ds_read_b128 v[72:75], v58 offset:34816
	ds_read_b128 v[124:127], v56 offset:2048
	ds_read_b128 v[128:131], v56 offset:4096
	ds_read_b128 v[132:135], v56 offset:6144
	ds_read_b128 v[136:139], v61
	s_waitcnt lgkmcnt(5)
	v_mfma_f32_16x16x32_bf16 v[30:33], v[64:67], v[68:71], v[30:33]
	s_waitcnt lgkmcnt(4)
	v_mfma_f32_16x16x32_bf16 v[26:29], v[64:67], v[72:75], v[26:29]
	ds_read_b128 v[64:67], v61 offset:2048
	s_waitcnt lgkmcnt(4)
	v_mfma_f32_16x16x32_bf16 v[22:25], v[124:127], v[68:71], v[22:25]
	v_mfma_f32_16x16x32_bf16 v[18:21], v[124:127], v[72:75], v[18:21]
	ds_read_b128 v[124:127], v61 offset:4096
	ds_read_b128 v[140:143], v60 offset:32768
	ds_read_b128 v[144:147], v60 offset:34816
	s_waitcnt lgkmcnt(6)
	v_mfma_f32_16x16x32_bf16 v[14:17], v[128:131], v[68:71], v[14:17]
	v_mfma_f32_16x16x32_bf16 v[10:13], v[128:131], v[72:75], v[10:13]
	ds_read_b128 v[128:131], v61 offset:6144
	s_waitcnt lgkmcnt(6)
	v_mfma_f32_16x16x32_bf16 v[6:9], v[132:135], v[68:71], v[6:9]
	v_mfma_f32_16x16x32_bf16 v[2:5], v[132:135], v[72:75], v[2:5]
	s_waitcnt lgkmcnt(1)
	v_mfma_f32_16x16x32_bf16 v[30:33], v[136:139], v[140:143], v[30:33]
	v_mfma_f32_16x16x32_bf16 v[26:29], v[136:139], v[144:147], v[26:29]
	s_waitcnt lgkmcnt(4)
	v_mfma_f32_16x16x32_bf16 v[22:25], v[64:67], v[140:143], v[22:25]
	v_mfma_f32_16x16x32_bf16 v[18:21], v[64:67], v[144:147], v[18:21]
	s_waitcnt lgkmcnt(3)
	v_mfma_f32_16x16x32_bf16 v[14:17], v[124:127], v[140:143], v[14:17]
	v_mfma_f32_16x16x32_bf16 v[10:13], v[124:127], v[144:147], v[10:13]
	s_waitcnt lgkmcnt(0)
	v_mfma_f32_16x16x32_bf16 v[6:9], v[128:131], v[140:143], v[6:9]
	v_mfma_f32_16x16x32_bf16 v[2:5], v[128:131], v[144:147], v[2:5]
	s_setprio 0
	s_barrier
; __device__ __forceinline__ float sigmoidf_(float x) { return 1.0f / (1.0f + __expf(-x)); }
; template <int MI, int NJ> ...
;     ...
;     for (int ks = 0; ks < 2; ++ks) {
;       const u16* a_ = ks ? a + dsw : a;
;       const u16* b_ = ks ? b + dsw : b;
;       bf16x8 bfr[NJ];
; #pragma unroll
;       for (int j = 0; j < NJ; ++j) bfr[j] = *(const bf16x8*)(b_ + j * 16 * 64);
; #pragma unroll
;       for (int ih = 0; ih < MI / 4; ++ih) {
;         bf16x8 af[4];
; #pragma unroll
;         for (int i = 0; i < 4; ++i) af[i] = *(const bf16x8*)(a_ + (ih * 4 + i) * 16 * 64);
; #pragma unroll
;         for (int i = 0; i < 4; ++i)
; #pragma unroll
;           for (int j = 0; j < NJ; ++j) acc[ih * 4 + i][j] = mfma16(af[i], bfr[j], acc[ih * 4 + i][j]);
;       }
;     }
;     __builtin_amdgcn_s_setprio(0);
;     __builtin_amdgcn_sched_barrier(0);
;     __syncthreads();
; __device__ __forceinline__ void phase_cmp1(const Params& p, u16* smem, volatile LAS unsigned* vb_) {
;     ...
; #pragma unroll
;     for (int i = 0; i < 4; ++i)
; #pragma unroll
;       for (int j = 0; j < 2; ++j) {
;         const int col = nt * 128 + wn * 32 + j * 16 + (lane & 15);
; #pragma unroll
;         for (int r = 0; r < 4; ++r) {
;           const int row = mt * 128 + wm * 64 + i * 16 + (lane >> 4) * 4 + r;
;           const float x = acc[i][j][r];
;           const float u = 0.7978845608028654f * (x + 0.044715f * x * x * x);
;           Hc[(size_t)row * 256 + col] = f2bf(x * sigmoidf_(2.0f * u));
	s_waitcnt vmcnt(12)
	ds_write_b128 v55, v[34:37]
	ds_write_b128 v55, v[38:41] offset:8192
	ds_write_b128 v55, v[42:45] offset:32768
	ds_write_b128 v55, v[46:49] offset:40960
	global_load_dwordx4 v[34:37], v[50:51], off offset:1024
	global_load_dwordx4 v[38:41], v[148:149], off offset:1024
	global_load_dwordx4 v[42:45], v[52:53], off offset:1024
	global_load_dwordx4 v[46:49], v[150:151], off offset:1024
	s_setprio 1
	ds_read_b128 v[68:71], v58 offset:49152
	ds_read_b128 v[64:67], v56 offset:16384
	ds_read_b128 v[72:75], v58 offset:51200
	ds_read_b128 v[124:127], v56 offset:18432
	ds_read_b128 v[128:131], v56 offset:20480
	ds_read_b128 v[132:135], v56 offset:22528
	ds_read_b128 v[136:139], v61 offset:16384
	s_waitcnt lgkmcnt(5)
	v_mfma_f32_16x16x32_bf16 v[30:33], v[64:67], v[68:71], v[30:33]
	s_waitcnt lgkmcnt(4)
	v_mfma_f32_16x16x32_bf16 v[26:29], v[64:67], v[72:75], v[26:29]
	ds_read_b128 v[64:67], v61 offset:18432
	s_waitcnt lgkmcnt(4)
	v_mfma_f32_16x16x32_bf16 v[22:25], v[124:127], v[68:71], v[22:25]
	v_mfma_f32_16x16x32_bf16 v[18:21], v[124:127], v[72:75], v[18:21]
	ds_read_b128 v[124:127], v61 offset:20480
	ds_read_b128 v[140:143], v60 offset:49152
	ds_read_b128 v[144:147], v60 offset:51200
	s_waitcnt lgkmcnt(6)
	v_mfma_f32_16x16x32_bf16 v[14:17], v[128:131], v[68:71], v[14:17]
	v_mfma_f32_16x16x32_bf16 v[10:13], v[128:131], v[72:75], v[10:13]
	ds_read_b128 v[128:131], v61 offset:22528
	s_waitcnt lgkmcnt(6)
	v_mfma_f32_16x16x32_bf16 v[6:9], v[132:135], v[68:71], v[6:9]
	v_mfma_f32_16x16x32_bf16 v[2:5], v[132:135], v[72:75], v[2:5]
	s_waitcnt lgkmcnt(1)
	v_mfma_f32_16x16x32_bf16 v[30:33], v[136:139], v[140:143], v[30:33]
	v_mfma_f32_16x16x32_bf16 v[26:29], v[136:139], v[144:147], v[26:29]
	s_waitcnt lgkmcnt(4)
	v_mfma_f32_16x16x32_bf16 v[22:25], v[64:67], v[140:143], v[22:25]
	v_mfma_f32_16x16x32_bf16 v[18:21], v[64:67], v[144:147], v[18:21]
	s_waitcnt lgkmcnt(3)
	v_mfma_f32_16x16x32_bf16 v[14:17], v[124:127], v[140:143], v[14:17]
	v_mfma_f32_16x16x32_bf16 v[10:13], v[124:127], v[144:147], v[10:13]
	s_waitcnt lgkmcnt(0)
	v_mfma_f32_16x16x32_bf16 v[6:9], v[128:131], v[140:143], v[6:9]
	v_mfma_f32_16x16x32_bf16 v[2:5], v[128:131], v[144:147], v[2:5]
	s_setprio 0
	s_add_i32 s21, s21, 4
	s_mov_b64 s[36:37], 0x200
	v_lshl_add_u64 v[50:51], v[50:51], 0, s[36:37]
	v_lshl_add_u64 v[148:149], v[148:149], 0, s[36:37]
	v_lshl_add_u64 v[52:53], v[52:53], 0, s[36:37]
	v_lshl_add_u64 v[150:151], v[150:151], 0, s[36:37]
	s_cmp_lg_u32 s21, 32
	s_barrier
	s_cbranch_scc1 .LBB0_436
	s_waitcnt vmcnt(0)
	s_waitcnt vmcnt(3)
	v_mul_f32_e32 v34, 0x3d372713, v30
	v_mul_f32_e32 v34, v30, v34
	v_fma_f32 v34, v30, v34, v30
	v_mul_f32_e32 v34, 0x3f4c422a, v34
	v_add_f32_e32 v34, v34, v34
	v_mul_f32_e32 v34, 0xbfb8aa3b, v34
	v_exp_f32_e32 v34, v34
	s_add_u32 s0, s75, s0
	v_readlane_b32 s12, v253, 0
	s_addc_u32 s1, s12, s1
	v_add_f32_e32 v37, 1.0, v34
	s_waitcnt vmcnt(2)
	v_div_scale_f32 v38, s[12:13], v37, v37, 1.0
	v_rcp_f32_e32 v39, v38
	v_add_u32_e32 v36, s11, v59
	v_or_b32_e32 v35, s20, v57
	v_lshlrev_b32_e32 v34, 1, v35
	v_fma_f32 v40, -v38, v39, 1.0
	v_fmac_f32_e32 v39, v40, v39
	v_div_scale_f32 v40, vcc, 1.0, v37, 1.0
	v_mul_f32_e32 v41, v40, v39
	s_waitcnt vmcnt(1)
	v_fma_f32 v42, -v38, v41, v40
	v_fmac_f32_e32 v41, v42, v39
	v_fma_f32 v38, -v38, v41, v40
	v_div_fmas_f32 v38, v38, v39, v41
	v_div_fixup_f32 v37, v38, v37, 1.0
	v_mul_f32_e32 v30, v30, v37
	v_mul_f32_e32 v37, 0x3d372713, v31
	v_mul_f32_e32 v37, v31, v37
	v_fma_f32 v37, v31, v37, v31
	v_mul_f32_e32 v37, 0x3f4c422a, v37
	v_add_f32_e32 v37, v37, v37
	v_mul_f32_e32 v37, 0xbfb8aa3b, v37
	v_exp_f32_e32 v40, v37
	v_ashrrev_i32_e32 v37, 31, v36
	v_mov_b32_e32 v35, v1
	v_lshlrev_b64 v[38:39], 9, v[36:37]
	v_add_f32_e32 v37, 1.0, v40
	v_lshl_add_u64 v[34:35], s[0:1], 0, v[34:35]
	v_cvt_pk_bf16_f32 v30, v30, s0
	v_div_scale_f32 v40, s[0:1], v37, v37, 1.0
	v_rcp_f32_e32 v41, v40
	v_lshl_add_u64 v[38:39], v[34:35], 0, v[38:39]
	global_store_short v[38:39], v30, off
	v_or_b32_e32 v30, 1, v36
	v_fma_f32 v42, -v40, v41, 1.0
	v_fmac_f32_e32 v41, v42, v41
	v_div_scale_f32 v42, vcc, 1.0, v37, 1.0
	v_mul_f32_e32 v43, v42, v41
	v_fma_f32 v44, -v40, v43, v42
	v_fmac_f32_e32 v43, v44, v41
	v_fma_f32 v40, -v40, v43, v42
	v_div_fmas_f32 v40, v40, v41, v43
	v_div_fixup_f32 v37, v40, v37, 1.0
	v_mul_f32_e32 v31, v31, v37
	v_mul_f32_e32 v37, 0x3d372713, v32
	v_mul_f32_e32 v37, v32, v37
	v_fma_f32 v37, v32, v37, v32
	v_mul_f32_e32 v37, 0x3f4c422a, v37
	v_add_f32_e32 v37, v37, v37
	v_mul_f32_e32 v37, 0xbfb8aa3b, v37
	v_exp_f32_e32 v37, v37
	v_cvt_pk_bf16_f32 v40, v31, s0
	v_ashrrev_i32_e32 v31, 31, v30
	v_lshlrev_b64 v[30:31], 9, v[30:31]
	v_add_f32_e32 v37, 1.0, v37
	v_div_scale_f32 v41, s[0:1], v37, v37, 1.0
	v_rcp_f32_e32 v42, v41
	v_lshl_add_u64 v[30:31], v[34:35], 0, v[30:31]
	global_store_short v[30:31], v40, off
	v_or_b32_e32 v40, 2, v36
	v_fma_f32 v43, -v41, v42, 1.0
	v_fmac_f32_e32 v42, v43, v42
	v_div_scale_f32 v43, vcc, 1.0, v37, 1.0
	v_mul_f32_e32 v44, v43, v42
	v_fma_f32 v45, -v41, v44, v43
	v_fmac_f32_e32 v44, v45, v42
	v_fma_f32 v41, -v41, v44, v43
	v_div_fmas_f32 v41, v41, v42, v44
	v_div_fixup_f32 v37, v41, v37, 1.0
	v_mul_f32_e32 v32, v32, v37
	v_mul_f32_e32 v37, 0x3d372713, v33
	v_mul_f32_e32 v37, v33, v37
	v_fma_f32 v37, v33, v37, v33
	v_mul_f32_e32 v37, 0x3f4c422a, v37
	v_add_f32_e32 v37, v37, v37
	v_mul_f32_e32 v37, 0xbfb8aa3b, v37
	v_exp_f32_e32 v37, v37
	v_cvt_pk_bf16_f32 v32, v32, s0
	v_ashrrev_i32_e32 v41, 31, v40
	v_lshlrev_b64 v[40:41], 9, v[40:41]
	v_add_f32_e32 v37, 1.0, v37
	v_div_scale_f32 v42, s[0:1], v37, v37, 1.0
	v_rcp_f32_e32 v43, v42
	v_lshl_add_u64 v[40:41], v[34:35], 0, v[40:41]
	global_store_short v[40:41], v32, off
	v_or_b32_e32 v32, 3, v36
	v_fma_f32 v44, -v42, v43, 1.0
	v_fmac_f32_e32 v43, v44, v43
	v_div_scale_f32 v44, vcc, 1.0, v37, 1.0
	v_mul_f32_e32 v45, v44, v43
	s_waitcnt vmcnt(3)
; __device__ __forceinline__ float sigmoidf_(float x) { return 1.0f / (1.0f + __expf(-x)); }
; __device__ __forceinline__ void phase_cmp1(const Params& p, u16* smem, volatile LAS unsigned* vb_) {
;     ...
; #pragma unroll
;     for (int i = 0; i < 4; ++i)
; #pragma unroll
;       for (int j = 0; j < 2; ++j) {
;         const int col = nt * 128 + wn * 32 + j * 16 + (lane & 15);
; #pragma unroll
;         for (int r = 0; r < 4; ++r) {
;           const int row = mt * 128 + wm * 64 + i * 16 + (lane >> 4) * 4 + r;
;           const float x = acc[i][j][r];
;           const float u = 0.7978845608028654f * (x + 0.044715f * x * x * x);
;           Hc[(size_t)row * 256 + col] = f2bf(x * sigmoidf_(2.0f * u));
;         }
;       }
	v_fma_f32 v46, -v42, v45, v44
	v_fmac_f32_e32 v45, v46, v43
	v_fma_f32 v42, -v42, v45, v44
	v_div_fmas_f32 v42, v42, v43, v45
	v_div_fixup_f32 v37, v42, v37, 1.0
	v_mul_f32_e32 v42, 0x3d372713, v26
	v_mul_f32_e32 v42, v26, v42
	v_fma_f32 v42, v26, v42, v26
	v_mul_f32_e32 v42, 0x3f4c422a, v42
	v_add_f32_e32 v42, v42, v42
	v_mul_f32_e32 v42, 0xbfb8aa3b, v42
	v_exp_f32_e32 v42, v42
	v_mul_f32_e32 v33, v33, v37
	v_cvt_pk_bf16_f32 v37, v33, s0
	v_ashrrev_i32_e32 v33, 31, v32
	v_add_f32_e32 v42, 1.0, v42
	v_div_scale_f32 v43, s[0:1], v42, v42, 1.0
	v_rcp_f32_e32 v44, v43
	v_lshlrev_b64 v[32:33], 9, v[32:33]
	v_lshl_add_u64 v[32:33], v[34:35], 0, v[32:33]
	global_store_short v[32:33], v37, off
	v_fma_f32 v37, -v43, v44, 1.0
	v_fmac_f32_e32 v44, v37, v44
	v_div_scale_f32 v37, vcc, 1.0, v42, 1.0
	v_mul_f32_e32 v45, v37, v44
	v_fma_f32 v46, -v43, v45, v37
	v_fmac_f32_e32 v45, v46, v44
	v_fma_f32 v37, -v43, v45, v37
	v_mul_f32_e32 v43, 0x3d372713, v27
	v_mul_f32_e32 v43, v27, v43
	v_fma_f32 v43, v27, v43, v27
	v_mul_f32_e32 v43, 0x3f4c422a, v43
	v_add_f32_e32 v43, v43, v43
	v_mul_f32_e32 v43, 0xbfb8aa3b, v43
	v_exp_f32_e32 v43, v43
	v_div_fmas_f32 v37, v37, v44, v45
	v_div_fixup_f32 v37, v37, v42, 1.0
	v_mul_f32_e32 v26, v26, v37
	v_add_f32_e32 v42, 1.0, v43
	v_div_scale_f32 v43, s[0:1], v42, v42, 1.0
	v_rcp_f32_e32 v44, v43
	s_nop 0
	v_cvt_pk_bf16_f32 v26, v26, s0
	global_store_short v[38:39], v26, off offset:32
	s_add_i32 s10, s10, s74
	v_fma_f32 v26, -v43, v44, 1.0
	v_fmac_f32_e32 v44, v26, v44
	v_div_scale_f32 v26, vcc, 1.0, v42, 1.0
	v_mul_f32_e32 v37, v26, v44
	v_fma_f32 v38, -v43, v37, v26
	v_fmac_f32_e32 v37, v38, v44
	v_mul_f32_e32 v38, 0x3d372713, v28
	v_mul_f32_e32 v38, v28, v38
	v_fma_f32 v38, v28, v38, v28
	v_mul_f32_e32 v38, 0x3f4c422a, v38
	v_add_f32_e32 v38, v38, v38
	v_mul_f32_e32 v38, 0xbfb8aa3b, v38
	v_exp_f32_e32 v38, v38
	v_fma_f32 v26, -v43, v37, v26
	v_div_fmas_f32 v26, v26, v44, v37
	v_div_fixup_f32 v26, v26, v42, 1.0
	v_add_f32_e32 v37, 1.0, v38
	v_div_scale_f32 v38, s[0:1], v37, v37, 1.0
	v_rcp_f32_e32 v39, v38
	v_mul_f32_e32 v26, v27, v26
	v_cvt_pk_bf16_f32 v26, v26, s0
	global_store_short v[30:31], v26, off offset:32
	v_fma_f32 v26, -v38, v39, 1.0
	v_fmac_f32_e32 v39, v26, v39
	v_div_scale_f32 v26, vcc, 1.0, v37, 1.0
	v_mul_f32_e32 v27, v26, v39
	v_fma_f32 v30, -v38, v27, v26
	v_fmac_f32_e32 v27, v30, v39
	v_mul_f32_e32 v30, 0x3d372713, v29
	v_mul_f32_e32 v30, v29, v30
	v_fma_f32 v30, v29, v30, v29
	v_mul_f32_e32 v30, 0x3f4c422a, v30
	v_add_f32_e32 v30, v30, v30
	v_mul_f32_e32 v30, 0xbfb8aa3b, v30
	v_exp_f32_e32 v30, v30
	v_fma_f32 v26, -v38, v27, v26
	v_div_fmas_f32 v26, v26, v39, v27
	v_div_fixup_f32 v26, v26, v37, 1.0
	v_add_f32_e32 v27, 1.0, v30
	v_div_scale_f32 v30, s[0:1], v27, v27, 1.0
	v_rcp_f32_e32 v31, v30
	v_mul_f32_e32 v26, v28, v26
	v_cvt_pk_bf16_f32 v26, v26, s0
	global_store_short v[40:41], v26, off offset:32
	v_fma_f32 v26, -v30, v31, 1.0
	v_fmac_f32_e32 v31, v26, v31
	v_div_scale_f32 v26, vcc, 1.0, v27, 1.0
	v_mul_f32_e32 v28, v26, v31
	v_fma_f32 v37, -v30, v28, v26
	v_fmac_f32_e32 v28, v37, v31
	v_fma_f32 v26, -v30, v28, v26
	v_mul_f32_e32 v30, 0x3d372713, v22
	v_mul_f32_e32 v30, v22, v30
	v_fma_f32 v30, v22, v30, v22
	v_mul_f32_e32 v30, 0x3f4c422a, v30
	v_add_f32_e32 v30, v30, v30
	v_mul_f32_e32 v30, 0xbfb8aa3b, v30
	v_exp_f32_e32 v30, v30
	v_div_fmas_f32 v26, v26, v31, v28
	v_div_fixup_f32 v26, v26, v27, 1.0
	v_mul_f32_e32 v26, v29, v26
	v_add_f32_e32 v27, 1.0, v30
	v_div_scale_f32 v28, s[0:1], v27, v27, 1.0
	v_rcp_f32_e32 v29, v28
	s_nop 0
	v_cvt_pk_bf16_f32 v26, v26, s0
	global_store_short v[32:33], v26, off offset:32
	v_or_b32_e32 v26, 16, v36
	v_fma_f32 v30, -v28, v29, 1.0
	v_fmac_f32_e32 v29, v30, v29
	v_div_scale_f32 v30, vcc, 1.0, v27, 1.0
	v_mul_f32_e32 v31, v30, v29
	v_fma_f32 v32, -v28, v31, v30
	v_fmac_f32_e32 v31, v32, v29
	v_fma_f32 v28, -v28, v31, v30
	v_div_fmas_f32 v28, v28, v29, v31
	v_div_fixup_f32 v27, v28, v27, 1.0
	v_mul_f32_e32 v22, v22, v27
	v_mul_f32_e32 v27, 0x3d372713, v23
	v_mul_f32_e32 v27, v23, v27
	v_fma_f32 v27, v23, v27, v23
	v_mul_f32_e32 v27, 0x3f4c422a, v27
	v_add_f32_e32 v27, v27, v27
	v_mul_f32_e32 v27, 0xbfb8aa3b, v27
	v_exp_f32_e32 v28, v27
	v_cvt_pk_bf16_f32 v22, v22, s0
	v_ashrrev_i32_e32 v27, 31, v26
	v_lshlrev_b64 v[26:27], 9, v[26:27]
	v_add_f32_e32 v28, 1.0, v28
	v_div_scale_f32 v29, s[0:1], v28, v28, 1.0
	v_rcp_f32_e32 v30, v29
	v_lshl_add_u64 v[26:27], v[34:35], 0, v[26:27]
	global_store_short v[26:27], v22, off
	v_or_b32_e32 v22, 17, v36
	v_fma_f32 v31, -v29, v30, 1.0
	v_fmac_f32_e32 v30, v31, v30
	v_div_scale_f32 v31, vcc, 1.0, v28, 1.0
	v_mul_f32_e32 v32, v31, v30
	v_fma_f32 v33, -v29, v32, v31
	v_fmac_f32_e32 v32, v33, v30
	v_fma_f32 v29, -v29, v32, v31
	v_div_fmas_f32 v29, v29, v30, v32
	v_div_fixup_f32 v28, v29, v28, 1.0
	v_mul_f32_e32 v23, v23, v28
	v_mul_f32_e32 v28, 0x3d372713, v24
	v_mul_f32_e32 v28, v24, v28
	v_fma_f32 v28, v24, v28, v24
	v_mul_f32_e32 v28, 0x3f4c422a, v28
	v_add_f32_e32 v28, v28, v28
	v_mul_f32_e32 v28, 0xbfb8aa3b, v28
	v_exp_f32_e32 v28, v28
	v_cvt_pk_bf16_f32 v29, v23, s0
	v_ashrrev_i32_e32 v23, 31, v22
	v_lshlrev_b64 v[22:23], 9, v[22:23]
	v_add_f32_e32 v30, 1.0, v28
	v_div_scale_f32 v31, s[0:1], v30, v30, 1.0
	v_rcp_f32_e32 v32, v31
	v_lshl_add_u64 v[22:23], v[34:35], 0, v[22:23]
	global_store_short v[22:23], v29, off
	v_or_b32_e32 v28, 18, v36
	v_fma_f32 v29, -v31, v32, 1.0
	v_fmac_f32_e32 v32, v29, v32
	v_div_scale_f32 v29, vcc, 1.0, v30, 1.0
	v_mul_f32_e32 v33, v29, v32
	v_fma_f32 v37, -v31, v33, v29
	v_fmac_f32_e32 v33, v37, v32
	v_fma_f32 v29, -v31, v33, v29
	v_div_fmas_f32 v29, v29, v32, v33
	v_div_fixup_f32 v29, v29, v30, 1.0
; __device__ __forceinline__ float sigmoidf_(float x) { return 1.0f / (1.0f + __expf(-x)); }
; __device__ __forceinline__ void phase_cmp1(const Params& p, u16* smem, volatile LAS unsigned* vb_) {
;     ...
; #pragma unroll
;     for (int i = 0; i < 4; ++i)
; #pragma unroll
;       for (int j = 0; j < 2; ++j) {
;         const int col = nt * 128 + wn * 32 + j * 16 + (lane & 15);
; #pragma unroll
;         for (int r = 0; r < 4; ++r) {
;           const int row = mt * 128 + wm * 64 + i * 16 + (lane >> 4) * 4 + r;
;           const float x = acc[i][j][r];
;           const float u = 0.7978845608028654f * (x + 0.044715f * x * x * x);
;           Hc[(size_t)row * 256 + col] = f2bf(x * sigmoidf_(2.0f * u));
;         }
;       }
	v_mul_f32_e32 v24, v24, v29
	v_mul_f32_e32 v29, 0x3d372713, v25
	v_mul_f32_e32 v29, v25, v29
	v_fma_f32 v29, v25, v29, v25
	v_mul_f32_e32 v29, 0x3f4c422a, v29
	v_add_f32_e32 v29, v29, v29
	v_mul_f32_e32 v29, 0xbfb8aa3b, v29
	v_exp_f32_e32 v30, v29
	v_cvt_pk_bf16_f32 v24, v24, s0
	v_ashrrev_i32_e32 v29, 31, v28
	v_lshlrev_b64 v[28:29], 9, v[28:29]
	v_add_f32_e32 v30, 1.0, v30
	v_div_scale_f32 v31, s[0:1], v30, v30, 1.0
	v_rcp_f32_e32 v32, v31
	v_lshl_add_u64 v[28:29], v[34:35], 0, v[28:29]
	global_store_short v[28:29], v24, off
	v_or_b32_e32 v24, 19, v36
	v_fma_f32 v33, -v31, v32, 1.0
	v_fmac_f32_e32 v32, v33, v32
	v_div_scale_f32 v33, vcc, 1.0, v30, 1.0
	v_mul_f32_e32 v37, v33, v32
	v_fma_f32 v38, -v31, v37, v33
	v_fmac_f32_e32 v37, v38, v32
	v_fma_f32 v31, -v31, v37, v33
	v_div_fmas_f32 v31, v31, v32, v37
	v_div_fixup_f32 v30, v31, v30, 1.0
	v_mul_f32_e32 v31, 0x3d372713, v18
	v_mul_f32_e32 v31, v18, v31
	v_fma_f32 v31, v18, v31, v18
	v_mul_f32_e32 v31, 0x3f4c422a, v31
	v_add_f32_e32 v31, v31, v31
	v_mul_f32_e32 v31, 0xbfb8aa3b, v31
	v_exp_f32_e32 v31, v31
	v_mul_f32_e32 v25, v25, v30
	v_cvt_pk_bf16_f32 v30, v25, s0
	v_ashrrev_i32_e32 v25, 31, v24
	v_add_f32_e32 v31, 1.0, v31
	v_div_scale_f32 v32, s[0:1], v31, v31, 1.0
	v_rcp_f32_e32 v33, v32
	v_lshlrev_b64 v[24:25], 9, v[24:25]
	v_lshl_add_u64 v[24:25], v[34:35], 0, v[24:25]
	global_store_short v[24:25], v30, off
	v_fma_f32 v30, -v32, v33, 1.0
	v_fmac_f32_e32 v33, v30, v33
	v_div_scale_f32 v30, vcc, 1.0, v31, 1.0
	v_mul_f32_e32 v37, v30, v33
	v_fma_f32 v38, -v32, v37, v30
	v_fmac_f32_e32 v37, v38, v33
	v_fma_f32 v30, -v32, v37, v30
	v_mul_f32_e32 v32, 0x3d372713, v19
	v_mul_f32_e32 v32, v19, v32
	v_fma_f32 v32, v19, v32, v19
	v_mul_f32_e32 v32, 0x3f4c422a, v32
	v_add_f32_e32 v32, v32, v32
	v_mul_f32_e32 v32, 0xbfb8aa3b, v32
	v_exp_f32_e32 v32, v32
	v_div_fmas_f32 v30, v30, v33, v37
	v_div_fixup_f32 v30, v30, v31, 1.0
	v_mul_f32_e32 v18, v18, v30
	v_add_f32_e32 v31, 1.0, v32
	v_div_scale_f32 v32, s[0:1], v31, v31, 1.0
	v_rcp_f32_e32 v33, v32
	s_nop 0
	v_cvt_pk_bf16_f32 v18, v18, s0
	global_store_short v[26:27], v18, off offset:32
	s_cmp_lt_i32 s10, 64
	v_fma_f32 v18, -v32, v33, 1.0
	v_fmac_f32_e32 v33, v18, v33
	v_div_scale_f32 v18, vcc, 1.0, v31, 1.0
	v_mul_f32_e32 v26, v18, v33
	v_fma_f32 v27, -v32, v26, v18
	v_fmac_f32_e32 v26, v27, v33
	v_mul_f32_e32 v27, 0x3d372713, v20
	v_mul_f32_e32 v27, v20, v27
	v_fma_f32 v27, v20, v27, v20
	v_mul_f32_e32 v27, 0x3f4c422a, v27
	v_add_f32_e32 v27, v27, v27
	v_mul_f32_e32 v27, 0xbfb8aa3b, v27
	v_exp_f32_e32 v27, v27
	v_fma_f32 v18, -v32, v26, v18
	v_div_fmas_f32 v18, v18, v33, v26
	v_div_fixup_f32 v18, v18, v31, 1.0
	v_add_f32_e32 v26, 1.0, v27
	v_div_scale_f32 v27, s[0:1], v26, v26, 1.0
	v_rcp_f32_e32 v30, v27
	v_mul_f32_e32 v18, v19, v18
	v_cvt_pk_bf16_f32 v18, v18, s0
	global_store_short v[22:23], v18, off offset:32
	v_fma_f32 v18, -v27, v30, 1.0
	v_fmac_f32_e32 v30, v18, v30
	v_div_scale_f32 v18, vcc, 1.0, v26, 1.0
	v_mul_f32_e32 v19, v18, v30
	v_fma_f32 v22, -v27, v19, v18
	v_fmac_f32_e32 v19, v22, v30
	v_mul_f32_e32 v22, 0x3d372713, v21
	v_mul_f32_e32 v22, v21, v22
	v_fma_f32 v22, v21, v22, v21
	v_mul_f32_e32 v22, 0x3f4c422a, v22
	v_add_f32_e32 v22, v22, v22
	v_mul_f32_e32 v22, 0xbfb8aa3b, v22
	v_exp_f32_e32 v22, v22
	v_fma_f32 v18, -v27, v19, v18
	v_div_fmas_f32 v18, v18, v30, v19
	v_div_fixup_f32 v18, v18, v26, 1.0
	v_add_f32_e32 v19, 1.0, v22
	v_div_scale_f32 v22, s[0:1], v19, v19, 1.0
	v_rcp_f32_e32 v23, v22
	v_mul_f32_e32 v18, v20, v18
	v_cvt_pk_bf16_f32 v18, v18, s0
	global_store_short v[28:29], v18, off offset:32
	v_fma_f32 v18, -v22, v23, 1.0
	v_fmac_f32_e32 v23, v18, v23
	v_div_scale_f32 v18, vcc, 1.0, v19, 1.0
	v_mul_f32_e32 v20, v18, v23
	v_fma_f32 v26, -v22, v20, v18
	v_fmac_f32_e32 v20, v26, v23
	v_fma_f32 v18, -v22, v20, v18
	v_mul_f32_e32 v22, 0x3d372713, v14
	v_mul_f32_e32 v22, v14, v22
	v_fma_f32 v22, v14, v22, v14
	v_mul_f32_e32 v22, 0x3f4c422a, v22
	v_add_f32_e32 v22, v22, v22
	v_mul_f32_e32 v22, 0xbfb8aa3b, v22
	v_exp_f32_e32 v22, v22
	v_div_fmas_f32 v18, v18, v23, v20
	v_div_fixup_f32 v18, v18, v19, 1.0
	v_mul_f32_e32 v18, v21, v18
	v_add_f32_e32 v19, 1.0, v22
	v_div_scale_f32 v20, s[0:1], v19, v19, 1.0
	v_rcp_f32_e32 v21, v20
	s_nop 0
	v_cvt_pk_bf16_f32 v18, v18, s0
	global_store_short v[24:25], v18, off offset:32
	v_or_b32_e32 v18, 32, v36
	v_fma_f32 v22, -v20, v21, 1.0
	v_fmac_f32_e32 v21, v22, v21
	v_div_scale_f32 v22, vcc, 1.0, v19, 1.0
	v_mul_f32_e32 v23, v22, v21
	v_fma_f32 v24, -v20, v23, v22
	v_fmac_f32_e32 v23, v24, v21
	v_fma_f32 v20, -v20, v23, v22
	v_div_fmas_f32 v20, v20, v21, v23
	v_div_fixup_f32 v19, v20, v19, 1.0
	v_mul_f32_e32 v14, v14, v19
	v_mul_f32_e32 v19, 0x3d372713, v15
	v_mul_f32_e32 v19, v15, v19
	v_fma_f32 v19, v15, v19, v15
	v_mul_f32_e32 v19, 0x3f4c422a, v19
	v_add_f32_e32 v19, v19, v19
	v_mul_f32_e32 v19, 0xbfb8aa3b, v19
	v_exp_f32_e32 v20, v19
	v_cvt_pk_bf16_f32 v14, v14, s0
	v_ashrrev_i32_e32 v19, 31, v18
	v_lshlrev_b64 v[18:19], 9, v[18:19]
	v_add_f32_e32 v20, 1.0, v20
	v_div_scale_f32 v21, s[0:1], v20, v20, 1.0
	v_rcp_f32_e32 v22, v21
	v_lshl_add_u64 v[18:19], v[34:35], 0, v[18:19]
	global_store_short v[18:19], v14, off
	v_or_b32_e32 v14, 33, v36
	v_fma_f32 v23, -v21, v22, 1.0
	v_fmac_f32_e32 v22, v23, v22
	v_div_scale_f32 v23, vcc, 1.0, v20, 1.0
	v_mul_f32_e32 v24, v23, v22
	v_fma_f32 v25, -v21, v24, v23
	v_fmac_f32_e32 v24, v25, v22
	v_fma_f32 v21, -v21, v24, v23
	v_div_fmas_f32 v21, v21, v22, v24
	v_div_fixup_f32 v20, v21, v20, 1.0
	v_mul_f32_e32 v15, v15, v20
	v_mul_f32_e32 v20, 0x3d372713, v16
	v_mul_f32_e32 v20, v16, v20
	v_fma_f32 v20, v16, v20, v16
	v_mul_f32_e32 v20, 0x3f4c422a, v20
; __device__ __forceinline__ float sigmoidf_(float x) { return 1.0f / (1.0f + __expf(-x)); }
; __device__ __forceinline__ void phase_cmp1(const Params& p, u16* smem, volatile LAS unsigned* vb_) {
;     ...
; #pragma unroll
;     for (int i = 0; i < 4; ++i)
; #pragma unroll
;       for (int j = 0; j < 2; ++j) {
;         const int col = nt * 128 + wn * 32 + j * 16 + (lane & 15);
; #pragma unroll
;         for (int r = 0; r < 4; ++r) {
;           const int row = mt * 128 + wm * 64 + i * 16 + (lane >> 4) * 4 + r;
;           const float x = acc[i][j][r];
;           const float u = 0.7978845608028654f * (x + 0.044715f * x * x * x);
;           Hc[(size_t)row * 256 + col] = f2bf(x * sigmoidf_(2.0f * u));
;         }
;       }
	v_add_f32_e32 v20, v20, v20
	v_mul_f32_e32 v20, 0xbfb8aa3b, v20
	v_exp_f32_e32 v20, v20
	v_cvt_pk_bf16_f32 v21, v15, s0
	v_ashrrev_i32_e32 v15, 31, v14
	v_lshlrev_b64 v[14:15], 9, v[14:15]
	v_add_f32_e32 v22, 1.0, v20
	v_div_scale_f32 v23, s[0:1], v22, v22, 1.0
	v_rcp_f32_e32 v24, v23
	v_lshl_add_u64 v[14:15], v[34:35], 0, v[14:15]
	global_store_short v[14:15], v21, off
	v_or_b32_e32 v20, 34, v36
	v_fma_f32 v21, -v23, v24, 1.0
	v_fmac_f32_e32 v24, v21, v24
	v_div_scale_f32 v21, vcc, 1.0, v22, 1.0
	v_mul_f32_e32 v25, v21, v24
	v_fma_f32 v26, -v23, v25, v21
	v_fmac_f32_e32 v25, v26, v24
	v_fma_f32 v21, -v23, v25, v21
	v_div_fmas_f32 v21, v21, v24, v25
	v_div_fixup_f32 v21, v21, v22, 1.0
	v_mul_f32_e32 v16, v16, v21
	v_mul_f32_e32 v21, 0x3d372713, v17
	v_mul_f32_e32 v21, v17, v21
	v_fma_f32 v21, v17, v21, v17
	v_mul_f32_e32 v21, 0x3f4c422a, v21
	v_add_f32_e32 v21, v21, v21
	v_mul_f32_e32 v21, 0xbfb8aa3b, v21
	v_exp_f32_e32 v22, v21
	v_cvt_pk_bf16_f32 v16, v16, s0
	v_ashrrev_i32_e32 v21, 31, v20
	v_lshlrev_b64 v[20:21], 9, v[20:21]
	v_add_f32_e32 v22, 1.0, v22
	v_div_scale_f32 v23, s[0:1], v22, v22, 1.0
	v_rcp_f32_e32 v24, v23
	v_lshl_add_u64 v[20:21], v[34:35], 0, v[20:21]
	global_store_short v[20:21], v16, off
	v_or_b32_e32 v16, 35, v36
	v_fma_f32 v25, -v23, v24, 1.0
	v_fmac_f32_e32 v24, v25, v24
	v_div_scale_f32 v25, vcc, 1.0, v22, 1.0
	v_mul_f32_e32 v26, v25, v24
	v_fma_f32 v27, -v23, v26, v25
	v_fmac_f32_e32 v26, v27, v24
	v_fma_f32 v23, -v23, v26, v25
	v_div_fmas_f32 v23, v23, v24, v26
	v_div_fixup_f32 v22, v23, v22, 1.0
	v_mul_f32_e32 v23, 0x3d372713, v10
	v_mul_f32_e32 v23, v10, v23
	v_fma_f32 v23, v10, v23, v10
	v_mul_f32_e32 v23, 0x3f4c422a, v23
	v_add_f32_e32 v23, v23, v23
	v_mul_f32_e32 v23, 0xbfb8aa3b, v23
	v_exp_f32_e32 v23, v23
	v_mul_f32_e32 v17, v17, v22
	v_cvt_pk_bf16_f32 v22, v17, s0
	v_ashrrev_i32_e32 v17, 31, v16
	v_add_f32_e32 v23, 1.0, v23
	v_div_scale_f32 v24, s[0:1], v23, v23, 1.0
	v_rcp_f32_e32 v25, v24
	v_lshlrev_b64 v[16:17], 9, v[16:17]
	v_lshl_add_u64 v[16:17], v[34:35], 0, v[16:17]
	global_store_short v[16:17], v22, off
	v_fma_f32 v22, -v24, v25, 1.0
	v_fmac_f32_e32 v25, v22, v25
	v_div_scale_f32 v22, vcc, 1.0, v23, 1.0
	v_mul_f32_e32 v26, v22, v25
	v_fma_f32 v27, -v24, v26, v22
	v_fmac_f32_e32 v26, v27, v25
	v_fma_f32 v22, -v24, v26, v22
	v_mul_f32_e32 v24, 0x3d372713, v11
	v_mul_f32_e32 v24, v11, v24
	v_fma_f32 v24, v11, v24, v11
	v_mul_f32_e32 v24, 0x3f4c422a, v24
	v_add_f32_e32 v24, v24, v24
	v_mul_f32_e32 v24, 0xbfb8aa3b, v24
	v_exp_f32_e32 v24, v24
	v_div_fmas_f32 v22, v22, v25, v26
	v_div_fixup_f32 v22, v22, v23, 1.0
	v_mul_f32_e32 v10, v10, v22
	v_add_f32_e32 v23, 1.0, v24
	v_div_scale_f32 v24, s[0:1], v23, v23, 1.0
	v_rcp_f32_e32 v25, v24
	s_nop 0
	v_cvt_pk_bf16_f32 v10, v10, s0
	global_store_short v[18:19], v10, off offset:32
	v_fma_f32 v10, -v24, v25, 1.0
	v_fmac_f32_e32 v25, v10, v25
	v_div_scale_f32 v10, vcc, 1.0, v23, 1.0
	v_mul_f32_e32 v18, v10, v25
	v_fma_f32 v19, -v24, v18, v10
	v_fmac_f32_e32 v18, v19, v25
	v_mul_f32_e32 v19, 0x3d372713, v12
	v_mul_f32_e32 v19, v12, v19
	v_fma_f32 v19, v12, v19, v12
	v_mul_f32_e32 v19, 0x3f4c422a, v19
	v_add_f32_e32 v19, v19, v19
	v_mul_f32_e32 v19, 0xbfb8aa3b, v19
	v_exp_f32_e32 v19, v19
	v_fma_f32 v10, -v24, v18, v10
	v_div_fmas_f32 v10, v10, v25, v18
	v_div_fixup_f32 v10, v10, v23, 1.0
	v_add_f32_e32 v18, 1.0, v19
	v_div_scale_f32 v19, s[0:1], v18, v18, 1.0
	v_rcp_f32_e32 v22, v19
	v_mul_f32_e32 v10, v11, v10
	v_cvt_pk_bf16_f32 v10, v10, s0
	global_store_short v[14:15], v10, off offset:32
	v_fma_f32 v10, -v19, v22, 1.0
	v_fmac_f32_e32 v22, v10, v22
	v_div_scale_f32 v10, vcc, 1.0, v18, 1.0
	v_mul_f32_e32 v11, v10, v22
	v_fma_f32 v14, -v19, v11, v10
	v_fmac_f32_e32 v11, v14, v22
	v_mul_f32_e32 v14, 0x3d372713, v13
	v_mul_f32_e32 v14, v13, v14
	v_fma_f32 v14, v13, v14, v13
	v_mul_f32_e32 v14, 0x3f4c422a, v14
	v_add_f32_e32 v14, v14, v14
	v_mul_f32_e32 v14, 0xbfb8aa3b, v14
	v_exp_f32_e32 v14, v14
	v_fma_f32 v10, -v19, v11, v10
	v_div_fmas_f32 v10, v10, v22, v11
	v_div_fixup_f32 v10, v10, v18, 1.0
	v_add_f32_e32 v11, 1.0, v14
	v_div_scale_f32 v14, s[0:1], v11, v11, 1.0
	v_rcp_f32_e32 v15, v14
	v_mul_f32_e32 v10, v12, v10
	v_cvt_pk_bf16_f32 v10, v10, s0
	global_store_short v[20:21], v10, off offset:32
	v_fma_f32 v10, -v14, v15, 1.0
	v_fmac_f32_e32 v15, v10, v15
	v_div_scale_f32 v10, vcc, 1.0, v11, 1.0
	v_mul_f32_e32 v12, v10, v15
	v_fma_f32 v18, -v14, v12, v10
	v_fmac_f32_e32 v12, v18, v15
	v_fma_f32 v10, -v14, v12, v10
	v_mul_f32_e32 v14, 0x3d372713, v6
	v_mul_f32_e32 v14, v6, v14
	v_fma_f32 v14, v6, v14, v6
	v_mul_f32_e32 v14, 0x3f4c422a, v14
	v_add_f32_e32 v14, v14, v14
	v_mul_f32_e32 v14, 0xbfb8aa3b, v14
	v_exp_f32_e32 v14, v14
	v_div_fmas_f32 v10, v10, v15, v12
	v_div_fixup_f32 v10, v10, v11, 1.0
	v_mul_f32_e32 v10, v13, v10
	v_add_f32_e32 v11, 1.0, v14
	v_div_scale_f32 v12, s[0:1], v11, v11, 1.0
	v_rcp_f32_e32 v13, v12
	s_nop 0
	v_cvt_pk_bf16_f32 v10, v10, s0
	global_store_short v[16:17], v10, off offset:32
	v_or_b32_e32 v10, 48, v36
	v_fma_f32 v14, -v12, v13, 1.0
	v_fmac_f32_e32 v13, v14, v13
	v_div_scale_f32 v14, vcc, 1.0, v11, 1.0
	v_mul_f32_e32 v15, v14, v13
	v_fma_f32 v16, -v12, v15, v14
	v_fmac_f32_e32 v15, v16, v13
	v_fma_f32 v12, -v12, v15, v14
	v_div_fmas_f32 v12, v12, v13, v15
	v_div_fixup_f32 v11, v12, v11, 1.0
	v_mul_f32_e32 v6, v6, v11
	v_mul_f32_e32 v11, 0x3d372713, v7
	v_mul_f32_e32 v11, v7, v11
	v_fma_f32 v11, v7, v11, v7
; __device__ __forceinline__ float sigmoidf_(float x) { return 1.0f / (1.0f + __expf(-x)); }
; __device__ __forceinline__ void phase_cmp1(const Params& p, u16* smem, volatile LAS unsigned* vb_) {
;     ...
; #pragma unroll
;     for (int i = 0; i < 4; ++i)
; #pragma unroll
;       for (int j = 0; j < 2; ++j) {
;         const int col = nt * 128 + wn * 32 + j * 16 + (lane & 15);
; #pragma unroll
;         for (int r = 0; r < 4; ++r) {
;           const int row = mt * 128 + wm * 64 + i * 16 + (lane >> 4) * 4 + r;
;           const float x = acc[i][j][r];
;           const float u = 0.7978845608028654f * (x + 0.044715f * x * x * x);
;           Hc[(size_t)row * 256 + col] = f2bf(x * sigmoidf_(2.0f * u));
;         }
;       }
;   }
	v_mul_f32_e32 v11, 0x3f4c422a, v11
	v_add_f32_e32 v11, v11, v11
	v_mul_f32_e32 v11, 0xbfb8aa3b, v11
	v_exp_f32_e32 v12, v11
	v_cvt_pk_bf16_f32 v6, v6, s0
	v_ashrrev_i32_e32 v11, 31, v10
	v_lshlrev_b64 v[10:11], 9, v[10:11]
	v_add_f32_e32 v12, 1.0, v12
	v_div_scale_f32 v13, s[0:1], v12, v12, 1.0
	v_rcp_f32_e32 v14, v13
	v_lshl_add_u64 v[10:11], v[34:35], 0, v[10:11]
	global_store_short v[10:11], v6, off
	v_or_b32_e32 v6, 49, v36
	v_fma_f32 v15, -v13, v14, 1.0
	v_fmac_f32_e32 v14, v15, v14
	v_div_scale_f32 v15, vcc, 1.0, v12, 1.0
	v_mul_f32_e32 v16, v15, v14
	v_fma_f32 v17, -v13, v16, v15
	v_fmac_f32_e32 v16, v17, v14
	v_fma_f32 v13, -v13, v16, v15
	v_div_fmas_f32 v13, v13, v14, v16
	v_div_fixup_f32 v12, v13, v12, 1.0
	v_mul_f32_e32 v7, v7, v12
	v_mul_f32_e32 v12, 0x3d372713, v8
	v_mul_f32_e32 v12, v8, v12
	v_fma_f32 v12, v8, v12, v8
	v_mul_f32_e32 v12, 0x3f4c422a, v12
	v_add_f32_e32 v12, v12, v12
	v_mul_f32_e32 v12, 0xbfb8aa3b, v12
	v_exp_f32_e32 v12, v12
	v_cvt_pk_bf16_f32 v13, v7, s0
	v_ashrrev_i32_e32 v7, 31, v6
	v_lshlrev_b64 v[6:7], 9, v[6:7]
	v_add_f32_e32 v14, 1.0, v12
	v_div_scale_f32 v15, s[0:1], v14, v14, 1.0
	v_rcp_f32_e32 v16, v15
	v_lshl_add_u64 v[6:7], v[34:35], 0, v[6:7]
	global_store_short v[6:7], v13, off
	v_or_b32_e32 v12, 50, v36
	v_fma_f32 v13, -v15, v16, 1.0
	v_fmac_f32_e32 v16, v13, v16
	v_div_scale_f32 v13, vcc, 1.0, v14, 1.0
	v_mul_f32_e32 v17, v13, v16
	v_fma_f32 v18, -v15, v17, v13
	v_fmac_f32_e32 v17, v18, v16
	v_fma_f32 v13, -v15, v17, v13
	v_div_fmas_f32 v13, v13, v16, v17
	v_div_fixup_f32 v13, v13, v14, 1.0
	v_mul_f32_e32 v8, v8, v13
	v_mul_f32_e32 v13, 0x3d372713, v9
	v_mul_f32_e32 v13, v9, v13
	v_fma_f32 v13, v9, v13, v9
	v_mul_f32_e32 v13, 0x3f4c422a, v13
	v_add_f32_e32 v13, v13, v13
	v_mul_f32_e32 v13, 0xbfb8aa3b, v13
	v_exp_f32_e32 v14, v13
	v_cvt_pk_bf16_f32 v8, v8, s0
	v_ashrrev_i32_e32 v13, 31, v12
	v_lshlrev_b64 v[12:13], 9, v[12:13]
	v_add_f32_e32 v14, 1.0, v14
	v_div_scale_f32 v15, s[0:1], v14, v14, 1.0
	v_rcp_f32_e32 v16, v15
	v_lshl_add_u64 v[12:13], v[34:35], 0, v[12:13]
	global_store_short v[12:13], v8, off
	v_or_b32_e32 v8, 51, v36
	v_fma_f32 v17, -v15, v16, 1.0
	v_fmac_f32_e32 v16, v17, v16
	v_div_scale_f32 v17, vcc, 1.0, v14, 1.0
	v_mul_f32_e32 v18, v17, v16
	v_fma_f32 v19, -v15, v18, v17
	v_fmac_f32_e32 v18, v19, v16
	v_fma_f32 v15, -v15, v18, v17
	v_div_fmas_f32 v15, v15, v16, v18
	v_div_fixup_f32 v14, v15, v14, 1.0
	v_mul_f32_e32 v15, 0x3d372713, v2
	v_mul_f32_e32 v15, v2, v15
	v_fma_f32 v15, v2, v15, v2
	v_mul_f32_e32 v15, 0x3f4c422a, v15
	v_add_f32_e32 v15, v15, v15
	v_mul_f32_e32 v15, 0xbfb8aa3b, v15
	v_exp_f32_e32 v15, v15
	v_mul_f32_e32 v9, v9, v14
	v_cvt_pk_bf16_f32 v14, v9, s0
	v_ashrrev_i32_e32 v9, 31, v8
	v_add_f32_e32 v15, 1.0, v15
	v_div_scale_f32 v16, s[0:1], v15, v15, 1.0
	v_rcp_f32_e32 v17, v16
	v_lshlrev_b64 v[8:9], 9, v[8:9]
	v_lshl_add_u64 v[8:9], v[34:35], 0, v[8:9]
	global_store_short v[8:9], v14, off
	v_fma_f32 v14, -v16, v17, 1.0
	v_fmac_f32_e32 v17, v14, v17
	v_div_scale_f32 v14, vcc, 1.0, v15, 1.0
	v_mul_f32_e32 v18, v14, v17
	v_fma_f32 v19, -v16, v18, v14
	v_fmac_f32_e32 v18, v19, v17
	v_fma_f32 v14, -v16, v18, v14
	v_mul_f32_e32 v16, 0x3d372713, v3
	v_mul_f32_e32 v16, v3, v16
	v_fma_f32 v16, v3, v16, v3
	v_mul_f32_e32 v16, 0x3f4c422a, v16
	v_add_f32_e32 v16, v16, v16
	v_mul_f32_e32 v16, 0xbfb8aa3b, v16
	v_exp_f32_e32 v16, v16
	v_div_fmas_f32 v14, v14, v17, v18
	v_div_fixup_f32 v14, v14, v15, 1.0
	v_mul_f32_e32 v2, v2, v14
	v_add_f32_e32 v15, 1.0, v16
	v_div_scale_f32 v16, s[0:1], v15, v15, 1.0
	v_rcp_f32_e32 v17, v16
	s_nop 0
	v_cvt_pk_bf16_f32 v2, v2, s0
	global_store_short v[10:11], v2, off offset:32
	v_fma_f32 v2, -v16, v17, 1.0
	v_fmac_f32_e32 v17, v2, v17
	v_div_scale_f32 v2, vcc, 1.0, v15, 1.0
	v_mul_f32_e32 v10, v2, v17
	v_fma_f32 v11, -v16, v10, v2
	v_fmac_f32_e32 v10, v11, v17
	v_mul_f32_e32 v11, 0x3d372713, v4
	v_mul_f32_e32 v11, v4, v11
	v_fma_f32 v11, v4, v11, v4
	v_mul_f32_e32 v11, 0x3f4c422a, v11
	v_add_f32_e32 v11, v11, v11
	v_mul_f32_e32 v11, 0xbfb8aa3b, v11
	v_exp_f32_e32 v11, v11
	v_fma_f32 v2, -v16, v10, v2
	v_div_fmas_f32 v2, v2, v17, v10
	v_div_fixup_f32 v2, v2, v15, 1.0
	v_add_f32_e32 v10, 1.0, v11
	v_div_scale_f32 v11, s[0:1], v10, v10, 1.0
	v_rcp_f32_e32 v14, v11
	v_mul_f32_e32 v2, v3, v2
	v_cvt_pk_bf16_f32 v2, v2, s0
	global_store_short v[6:7], v2, off offset:32
	v_fma_f32 v2, -v11, v14, 1.0
	v_fmac_f32_e32 v14, v2, v14
	v_div_scale_f32 v2, vcc, 1.0, v10, 1.0
	v_mul_f32_e32 v3, v2, v14
	v_fma_f32 v6, -v11, v3, v2
	v_fmac_f32_e32 v3, v6, v14
	v_mul_f32_e32 v6, 0x3d372713, v5
	v_mul_f32_e32 v6, v5, v6
	v_fma_f32 v6, v5, v6, v5
	v_mul_f32_e32 v6, 0x3f4c422a, v6
	v_add_f32_e32 v6, v6, v6
	v_mul_f32_e32 v6, 0xbfb8aa3b, v6
	v_exp_f32_e32 v6, v6
	v_fma_f32 v2, -v11, v3, v2
	v_div_fmas_f32 v2, v2, v14, v3
	v_div_fixup_f32 v2, v2, v10, 1.0
	v_add_f32_e32 v3, 1.0, v6
	v_div_scale_f32 v6, s[0:1], v3, v3, 1.0
	v_rcp_f32_e32 v7, v6
	v_mul_f32_e32 v2, v4, v2
	v_cvt_pk_bf16_f32 v2, v2, s0
	global_store_short v[12:13], v2, off offset:32
	v_fma_f32 v2, -v6, v7, 1.0
	v_fmac_f32_e32 v7, v2, v7
	v_div_scale_f32 v2, vcc, 1.0, v3, 1.0
	v_mul_f32_e32 v4, v2, v7
	v_fma_f32 v10, -v6, v4, v2
	v_fmac_f32_e32 v4, v10, v7
	v_fma_f32 v2, -v6, v4, v2
	v_div_fmas_f32 v2, v2, v7, v4
	v_div_fixup_f32 v2, v2, v3, 1.0
	v_mul_f32_e32 v2, v5, v2
	v_cvt_pk_bf16_f32 v2, v2, s0
	global_store_short v[8:9], v2, off offset:32
	s_cbranch_scc1 .LBB0_435
